# first rows phase: input pointer selected from scalar-loaded pointers instead of a vector pointer load plus full wait per row
# speedup vs baseline: 1.0001x; 1.0001x over previous
.LBB0_446:
	s_mov_b64 s[2:3], s[36:37]
	s_waitcnt vmcnt(0)
	v_mov_b32_e32 v0, v224
	s_load_dwordx4 s[48:51], s[2:3], 0xa0
	s_load_dwordx2 s[26:27], s[2:3], 0x0
	s_load_dwordx2 s[28:29], s[2:3], 0x8
	s_cmp_eq_u64 s[14:15], 0
	v_lshlrev_b32_e32 v1, 3, v0
	s_cselect_b64 s[20:21], -1, 0
	s_cmp_lg_u64 s[14:15], 0
	v_and_b32_e32 v32, 0x1f8, v1
	v_readlane_b32 s10, v253, 0
	s_mov_b32 s13, s54
	s_cselect_b64 s[6:7], -1, 0
	s_waitcnt vmcnt(1)
	v_mov_b32_e32 v96, 0
	s_and_b64 vcc, exec, s[20:21]
	v_lshlrev_b32_e32 v34, 2, v32
	v_mov_b32_e32 v98, 0
	s_cbranch_vccnz .LBB0_448
	global_load_dword v98, v34, s[0:1]

.LBB0_538:
	v_mov_b64_e32 v[70:71], v[18:19]
	v_mov_b64_e32 v[66:67], v[22:23]
	v_mov_b64_e32 v[58:59], v[2:3]
	v_mov_b64_e32 v[54:55], v[6:7]
	s_andn2_b64 vcc, exec, s[4:5]
	v_mov_b64_e32 v[68:69], v[16:17]
	v_mov_b64_e32 v[64:65], v[20:21]
	v_mov_b64_e32 v[56:57], v[0:1]
	v_mov_b64_e32 v[52:53], v[4:5]
	s_cbranch_vccnz .LBB0_540
	v_cmp_gt_i32_e32 vcc, s33, v88
	s_waitcnt vmcnt(1)
	v_add_u32_e32 v48, 0xffffc000, v88
	v_mov_b32_e32 v141, v113
	v_mov_b32_e32 v50, s26
	v_mov_b32_e32 v51, s27
	v_mov_b32_e32 v60, s28
	v_mov_b32_e32 v61, s29
	v_cndmask_b32_e32 v50, v60, v50, vcc
	v_cndmask_b32_e32 v51, v61, v51, vcc
	v_cndmask_b32_e32 v49, 0, v89, vcc
	v_cndmask_b32_e32 v48, v48, v88, vcc
	v_lshlrev_b64 v[48:49], 12, v[48:49]
	v_mov_b64_e32 v[62:63], v[14:15]
	v_mov_b64_e32 v[60:61], v[12:13]
	v_lshl_add_u64 v[48:49], v[50:51], 0, v[48:49]
	v_lshl_add_u64 v[48:49], v[48:49], 0, v[140:141]
	global_load_dwordx4 v[56:59], v[48:49], off offset:16 nt
	global_load_dwordx4 v[52:55], v[48:49], off nt
	global_load_dwordx4 v[68:71], v[48:49], off offset:2064 nt
	global_load_dwordx4 v[64:67], v[48:49], off offset:2048 nt
	v_mov_b64_e32 v[50:51], v[10:11]
	v_mov_b64_e32 v[48:49], v[8:9]
